# grid barrier: non-leader workgroups poll the cross-XCD release generation directly (no per-XCD relay hop); leaders no longer publish the relay word
# speedup vs baseline: 1.0123x; 1.0123x over previous
.LBB0_143:
	s_or_b64 exec, exec, s[10:11]
	v_cvt_f32_u32_e32 v4, v2
	s_waitcnt vmcnt(0)
	v_readfirstlane_b32 s8, v3
	v_sub_u32_e32 v3, 0, v2
	v_rcp_iflag_f32_e32 v4, v4
	v_add_u32_e32 v5, s8, v1
	v_mul_f32_e32 v4, 0x4f7ffffe, v4
	v_cvt_u32_f32_e32 v4, v4
	v_mul_lo_u32 v1, v3, v4
	v_mul_hi_u32 v1, v4, v1
	v_add_u32_e32 v1, v4, v1
	v_mul_hi_u32 v1, v5, v1
	v_mul_lo_u32 v3, v1, v2
	v_sub_u32_e32 v3, v5, v3
	v_add_u32_e32 v4, 1, v1
	v_cmp_ge_u32_e32 vcc, v3, v2
	s_nop 1
	v_cndmask_b32_e32 v1, v1, v4, vcc
	v_sub_u32_e32 v4, v3, v2
	v_cndmask_b32_e32 v3, v3, v4, vcc
	v_add_u32_e32 v4, 1, v1
	v_cmp_ge_u32_e32 vcc, v3, v2
	v_add_u32_e32 v3, 1, v5
	s_nop 0
	v_cndmask_b32_e32 v1, v1, v4, vcc
	v_mul_lo_u32 v4, v2, v1
	v_add_u32_e32 v2, v4, v2
	v_cmp_ne_u32_e32 vcc, v3, v2
	s_and_saveexec_b64 s[8:9], vcc
	s_xor_b64 s[8:9], exec, s[8:9]
	s_cbranch_execz .LBB0_157
	s_waitcnt lgkmcnt(0)
	v_mov_b32_e32 v0, 0
	s_add_u32 s12, s4, 0x3500
	s_addc_u32 s13, s5, 0
	global_load_dword v0, v0, s[12:13] sc1
	s_waitcnt vmcnt(0)
	v_cmp_eq_u32_e32 vcc, v0, v1
	s_and_saveexec_b64 s[10:11], vcc
	s_cbranch_execz .LBB0_156
	s_mov_b32 s24, 1
	s_mov_b64 s[14:15], 0
	v_mov_b32_e32 v0, 0
	s_branch .LBB0_147

.LBB0_174:
	s_or_b64 exec, exec, s[4:5]
	s_mov_b64 s[4:5], exec
	v_mbcnt_lo_u32_b32 v0, s4, 0
	v_mbcnt_hi_u32_b32 v0, s5, v0
	v_cmp_eq_u32_e32 vcc, 0, v0
	s_waitcnt vmcnt(0)
	buffer_inv sc1
	s_and_saveexec_b64 s[8:9], vcc
	s_cbranch_execz .LBB0_176
	s_bcnt1_i32_b64 s4, s[4:5]
	v_mov_b32_e32 v0, 0x2000
	v_mov_b32_e32 v1, s4
.LBB0_176:
	s_or_b64 exec, exec, s[8:9]
	s_waitcnt vmcnt(0)

.LBB0_336:
	s_or_b64 exec, exec, s[4:5]
	s_mov_b64 s[4:5], exec
	v_mbcnt_lo_u32_b32 v0, s4, 0
	v_mbcnt_hi_u32_b32 v0, s5, v0
	v_cmp_eq_u32_e32 vcc, 0, v0
	s_waitcnt vmcnt(0)
	buffer_inv sc1
	s_and_saveexec_b64 s[8:9], vcc
	s_cbranch_execz .LBB0_338
	s_bcnt1_i32_b64 s4, s[4:5]
	v_mov_b32_e32 v0, 0x2000
	v_mov_b32_e32 v1, s4
.LBB0_338:
	s_or_b64 exec, exec, s[8:9]
	s_waitcnt vmcnt(0)

.LBB0_403:
	s_or_b64 exec, exec, s[4:5]
	s_mov_b64 s[4:5], exec
	v_mbcnt_lo_u32_b32 v0, s4, 0
	v_mbcnt_hi_u32_b32 v0, s5, v0
	v_cmp_eq_u32_e32 vcc, 0, v0
	s_waitcnt vmcnt(0)
	buffer_inv sc1
	s_and_saveexec_b64 s[8:9], vcc
	s_cbranch_execz .LBB0_405
	s_bcnt1_i32_b64 s4, s[4:5]
	v_mov_b32_e32 v0, 0x2000
	v_mov_b32_e32 v1, s4
.LBB0_405:
	s_or_b64 exec, exec, s[8:9]
	s_waitcnt vmcnt(0)

.LBB0_447:
	s_or_b64 exec, exec, s[12:13]
	v_cvt_f32_u32_e32 v4, v2
	s_waitcnt vmcnt(0)
	v_readfirstlane_b32 s3, v3
	v_sub_u32_e32 v3, 0, v2
	v_rcp_iflag_f32_e32 v4, v4
	v_add_u32_e32 v5, s3, v1
	v_mul_f32_e32 v4, 0x4f7ffffe, v4
	v_cvt_u32_f32_e32 v4, v4
	v_mul_lo_u32 v1, v3, v4
	v_mul_hi_u32 v1, v4, v1
	v_add_u32_e32 v1, v4, v1
	v_mul_hi_u32 v1, v5, v1
	v_mul_lo_u32 v3, v1, v2
	v_sub_u32_e32 v3, v5, v3
	v_add_u32_e32 v4, 1, v1
	v_cmp_ge_u32_e32 vcc, v3, v2
	s_nop 1
	v_cndmask_b32_e32 v1, v1, v4, vcc
	v_sub_u32_e32 v4, v3, v2
	v_cndmask_b32_e32 v3, v3, v4, vcc
	v_add_u32_e32 v4, 1, v1
	v_cmp_ge_u32_e32 vcc, v3, v2
	v_add_u32_e32 v3, 1, v5
	s_nop 0
	v_cndmask_b32_e32 v1, v1, v4, vcc
	v_mul_lo_u32 v4, v2, v1
	v_add_u32_e32 v2, v4, v2
	v_cmp_ne_u32_e32 vcc, v3, v2
	s_and_saveexec_b64 s[10:11], vcc
	s_xor_b64 s[10:11], exec, s[10:11]
	s_cbranch_execz .LBB0_461
	s_waitcnt lgkmcnt(0)
	s_add_u32 s14, s6, 0x3500
	s_addc_u32 s15, s7, 0
	global_load_dword v0, v145, s[14:15] sc1
	s_waitcnt vmcnt(0)
	v_cmp_eq_u32_e32 vcc, v0, v1
	s_and_saveexec_b64 s[12:13], vcc
	s_cbranch_execz .LBB0_460
	s_mov_b32 s3, 1
	s_mov_b64 s[16:17], 0
	s_branch .LBB0_451

.LBB0_478:
	s_or_b64 exec, exec, s[6:7]
	s_mov_b64 s[6:7], exec
	v_mbcnt_lo_u32_b32 v0, s6, 0
	v_mbcnt_hi_u32_b32 v0, s7, v0
	v_cmp_eq_u32_e32 vcc, 0, v0
	s_waitcnt vmcnt(0)
	buffer_inv sc1
	s_and_saveexec_b64 s[10:11], vcc
	s_cbranch_execz .LBB0_480
	s_bcnt1_i32_b64 s3, s[6:7]
	v_mov_b32_e32 v0, s3
.LBB0_480:
	s_or_b64 exec, exec, s[10:11]
	s_waitcnt vmcnt(0)

.LBB0_676:
	s_or_b64 exec, exec, s[6:7]
	s_mov_b64 s[6:7], exec
	v_mbcnt_lo_u32_b32 v0, s6, 0
	v_mbcnt_hi_u32_b32 v0, s7, v0
	v_cmp_eq_u32_e32 vcc, 0, v0
	s_waitcnt vmcnt(0)
	buffer_inv sc1
	s_and_saveexec_b64 s[10:11], vcc
	s_cbranch_execz .LBB0_678
	s_bcnt1_i32_b64 s3, s[6:7]
	v_mov_b32_e32 v0, s3
.LBB0_678:
	s_or_b64 exec, exec, s[10:11]
	s_waitcnt vmcnt(0)

.LBB0_1053:
	s_or_b64 exec, exec, s[6:7]
	s_mov_b64 s[6:7], exec
	v_mbcnt_lo_u32_b32 v0, s6, 0
	v_mbcnt_hi_u32_b32 v0, s7, v0
	v_cmp_eq_u32_e32 vcc, 0, v0
	s_waitcnt vmcnt(0)
	buffer_inv sc1
	s_and_saveexec_b64 s[10:11], vcc
	s_cbranch_execz .LBB0_1055
	s_bcnt1_i32_b64 s3, s[6:7]
	v_mov_b32_e32 v0, s3
.LBB0_1055:
	s_or_b64 exec, exec, s[10:11]
	s_waitcnt vmcnt(0)

.LBB0_1142:
	s_or_b64 exec, exec, s[6:7]
	s_mov_b64 s[6:7], exec
	v_mbcnt_lo_u32_b32 v0, s6, 0
	v_mbcnt_hi_u32_b32 v0, s7, v0
	v_cmp_eq_u32_e32 vcc, 0, v0
	s_waitcnt vmcnt(0)
	buffer_inv sc1
	s_and_saveexec_b64 s[10:11], vcc
	s_cbranch_execz .LBB0_1144
	s_bcnt1_i32_b64 s3, s[6:7]
	v_mov_b32_e32 v0, s3
.LBB0_1144:
	s_or_b64 exec, exec, s[10:11]
	s_waitcnt vmcnt(0)

.LBB0_1216:
	s_or_b64 exec, exec, s[6:7]
	s_mov_b64 s[6:7], exec
	v_mbcnt_lo_u32_b32 v0, s6, 0
	v_mbcnt_hi_u32_b32 v0, s7, v0
	v_cmp_eq_u32_e32 vcc, 0, v0
	s_waitcnt vmcnt(0)
	buffer_inv sc1
	s_and_saveexec_b64 s[10:11], vcc
	s_cbranch_execz .LBB0_1218
	s_bcnt1_i32_b64 s3, s[6:7]
	v_mov_b32_e32 v0, s3
.LBB0_1218:
	s_or_b64 exec, exec, s[10:11]
	s_waitcnt vmcnt(0)

.LBB0_1284:
	s_or_b64 exec, exec, s[6:7]
	s_mov_b64 s[6:7], exec
	v_mbcnt_lo_u32_b32 v0, s6, 0
	v_mbcnt_hi_u32_b32 v0, s7, v0
	v_cmp_eq_u32_e32 vcc, 0, v0
	s_waitcnt vmcnt(0)
	buffer_inv sc1
	s_and_saveexec_b64 s[10:11], vcc
	s_cbranch_execz .LBB0_1286
	s_bcnt1_i32_b64 s3, s[6:7]
	v_mov_b32_e32 v0, s3
.LBB0_1286:
	s_or_b64 exec, exec, s[10:11]
	s_waitcnt vmcnt(0)

.LBB0_1357:
	s_or_b64 exec, exec, s[6:7]
	s_mov_b64 s[6:7], exec
	v_mbcnt_lo_u32_b32 v0, s6, 0
	v_mbcnt_hi_u32_b32 v0, s7, v0
	v_cmp_eq_u32_e32 vcc, 0, v0
	s_waitcnt vmcnt(0)
	buffer_inv sc1
	s_and_saveexec_b64 s[10:11], vcc
	s_cbranch_execz .LBB0_1359
	s_bcnt1_i32_b64 s3, s[6:7]
	v_mov_b32_e32 v0, s3
.LBB0_1359:
	s_or_b64 exec, exec, s[10:11]
	s_waitcnt vmcnt(0)

.LBB0_1400:
	s_or_b64 exec, exec, s[14:15]
	v_cvt_f32_u32_e32 v4, v2
	s_waitcnt vmcnt(0)
	v_readfirstlane_b32 s3, v3
	v_sub_u32_e32 v3, 0, v2
	v_rcp_iflag_f32_e32 v4, v4
	v_add_u32_e32 v5, s3, v1
	v_mul_f32_e32 v4, 0x4f7ffffe, v4
	v_cvt_u32_f32_e32 v4, v4
	v_mul_lo_u32 v1, v3, v4
	v_mul_hi_u32 v1, v4, v1
	v_add_u32_e32 v1, v4, v1
	v_mul_hi_u32 v1, v5, v1
	v_mul_lo_u32 v3, v1, v2
	v_sub_u32_e32 v3, v5, v3
	v_add_u32_e32 v4, 1, v1
	v_cmp_ge_u32_e32 vcc, v3, v2
	s_nop 1
	v_cndmask_b32_e32 v1, v1, v4, vcc
	v_sub_u32_e32 v4, v3, v2
	v_cndmask_b32_e32 v3, v3, v4, vcc
	v_add_u32_e32 v4, 1, v1
	v_cmp_ge_u32_e32 vcc, v3, v2
	v_add_u32_e32 v3, 1, v5
	s_nop 0
	v_cndmask_b32_e32 v1, v1, v4, vcc
	v_mul_lo_u32 v4, v2, v1
	v_add_u32_e32 v2, v4, v2
	v_cmp_ne_u32_e32 vcc, v3, v2
	s_and_saveexec_b64 s[12:13], vcc
	s_xor_b64 s[12:13], exec, s[12:13]
	s_cbranch_execz .LBB0_1414
	s_waitcnt lgkmcnt(0)
	s_add_u32 s16, s8, 0x3500
	s_addc_u32 s17, s9, 0
	global_load_dword v0, v145, s[16:17] sc1
	s_waitcnt vmcnt(0)
	v_cmp_eq_u32_e32 vcc, v0, v1
	s_and_saveexec_b64 s[14:15], vcc
	s_cbranch_execz .LBB0_1413
	s_mov_b32 s3, 1
	s_mov_b64 s[18:19], 0
	s_branch .LBB0_1404

.LBB0_1431:
	s_or_b64 exec, exec, s[8:9]
	s_mov_b64 s[8:9], exec
	v_mbcnt_lo_u32_b32 v0, s8, 0
	v_mbcnt_hi_u32_b32 v0, s9, v0
	v_cmp_eq_u32_e32 vcc, 0, v0
	s_waitcnt vmcnt(0)
	buffer_inv sc1
	s_and_saveexec_b64 s[12:13], vcc
	s_cbranch_execz .LBB0_1433
	s_bcnt1_i32_b64 s3, s[8:9]
	v_mov_b32_e32 v0, s3
.LBB0_1433:
	s_or_b64 exec, exec, s[12:13]
	s_waitcnt vmcnt(0)

.LBB0_1539:
	s_or_b64 exec, exec, s[8:9]
	s_mov_b64 s[8:9], exec
	v_mbcnt_lo_u32_b32 v0, s8, 0
	v_mbcnt_hi_u32_b32 v0, s9, v0
	v_cmp_eq_u32_e32 vcc, 0, v0
	s_waitcnt vmcnt(0)
	buffer_inv sc1
	s_and_saveexec_b64 s[12:13], vcc
	s_cbranch_execz .LBB0_409
	s_bcnt1_i32_b64 s3, s[8:9]
	v_mov_b32_e32 v0, s3
	s_branch .LBB0_409
